# v17 + softmax row-sum accumulation: packed v_pk_add_f32 pairs split into plain v_add_f32 (same arithmetic, avoids packed-op issue penalty beside MFMAs)
# baseline (speedup 1.0000x reference)
.LBB0_43:
	s_cmp_le_i32 s51, s29
	s_cselect_b64 s[52:53], -1, 0
	s_cmp_ge_i32 s92, s49
	s_cselect_b64 s[54:55], -1, 0
	s_or_b64 s[52:53], s[54:55], s[52:53]
	s_and_b64 vcc, exec, s[52:53]
	s_cbranch_vccnz .LBB0_46
	s_mul_i32 s52, s50, 0xac00
	s_add_i32 s52, s52, 0
	v_add_u32_e32 v177, s52, v166
	ds_read_b128 v[178:181], v177
	ds_read_b128 v[182:185], v177 offset:32
	ds_read_b128 v[186:189], v177 offset:64
	s_waitcnt lgkmcnt(2)
	v_mfma_f32_32x32x16_bf16 v[82:97], v[178:181], v[98:101], v[230:245]
	ds_read_b128 v[178:181], v177 offset:96
	s_waitcnt lgkmcnt(2)
	v_mfma_f32_32x32x16_bf16 v[82:97], v[182:185], v[102:105], v[82:97]
	ds_read_b128 v[182:185], v177 offset:128
	s_waitcnt lgkmcnt(2)
	v_mfma_f32_32x32x16_bf16 v[82:97], v[186:189], v[106:109], v[82:97]
	ds_read_b128 v[186:189], v177 offset:160
	s_waitcnt lgkmcnt(2)
	v_mfma_f32_32x32x16_bf16 v[82:97], v[178:181], v[110:113], v[82:97]
	ds_read_b128 v[178:181], v177 offset:192
	ds_read_b128 v[190:193], v177 offset:224
	s_waitcnt lgkmcnt(3)
	v_mfma_f32_32x32x16_bf16 v[82:97], v[182:185], v[114:117], v[82:97]
	global_load_dwordx4 v[182:185], v[162:163], off offset:-128
	ds_read_b128 v[194:197], v177 offset:8704
	s_waitcnt lgkmcnt(3)
	v_mfma_f32_32x32x16_bf16 v[82:97], v[186:189], v[118:121], v[82:97]
	global_load_dwordx4 v[186:189], v[162:163], off offset:-112
	s_waitcnt lgkmcnt(2)
	v_mfma_f32_32x32x16_bf16 v[82:97], v[178:181], v[122:125], v[82:97]
	global_load_dwordx4 v[178:181], v[162:163], off offset:-64
	global_load_dwordx4 v[198:201], v[162:163], off offset:-48
	ds_read_b128 v[202:205], v177 offset:8736
	global_load_dwordx4 v[218:221], v[162:163], off
	ds_read_b128 v[214:217], v177 offset:8768
	s_waitcnt lgkmcnt(3)
	v_mfma_f32_32x32x16_bf16 v[82:97], v[190:193], v[126:129], v[82:97]
	v_add3_u32 v228, s52, v167, v165
	ds_read_b128 v[190:193], v177 offset:8800
	s_waitcnt lgkmcnt(3)
	v_mfma_f32_32x32x16_bf16 v[66:81], v[194:197], v[98:101], v[230:245]
	s_waitcnt vmcnt(4)
	s_nop 6
	v_add_f32_e32 v0, v182, v82
	v_add_f32_e32 v82, v183, v83
	v_exp_f32_e32 v83, v0
	v_exp_f32_e32 v182, v82
	v_max_f32_e32 v226, v0, v82
	v_add_f32_e32 v183, v83, v182
	v_cvt_pk_bf16_f32 v82, v83, v182
	ds_read_b128 v[194:197], v177 offset:8832
	s_waitcnt lgkmcnt(3)
	v_mfma_f32_32x32x16_bf16 v[66:81], v[202:205], v[102:105], v[66:81]
	v_add_f32_e32 v83, v184, v84
	v_add_f32_e32 v84, v185, v85
	global_load_dwordx4 v[202:205], v[162:163], off offset:16
	v_exp_f32_e32 v182, v83
	v_exp_f32_e32 v0, v84
	v_max_f32_e32 v83, v83, v84
	v_max3_f32 v229, v226, s86, v83
	v_add_f32_e32 v84, v182, v0
	v_add_f32_e32 v85, v183, v1
	v_cvt_pk_bf16_f32 v83, v182, v0
	v_add_f32_e32 v227, v84, v85
	ds_read_b128 v[182:185], v177 offset:8864
	s_waitcnt vmcnt(4)
	v_add_f32_e32 v0, v186, v86
	v_add_f32_e32 v84, v187, v87
	v_exp_f32_e32 v85, v0
	v_exp_f32_e32 v86, v84
	s_waitcnt lgkmcnt(3)
	v_mfma_f32_32x32x16_bf16 v[66:81], v[214:217], v[106:109], v[66:81]
	v_max_f32_e32 v0, v0, v84
	v_add_f32_e32 v87, v85, v86
	v_cvt_pk_bf16_f32 v84, v85, v86
	ds_read_b128 v[214:217], v177 offset:8896
	v_add_f32_e32 v85, v188, v88
	v_add_f32_e32 v88, v189, v89
	global_load_dwordx4 v[186:189], v[162:163], off offset:64
	s_waitcnt lgkmcnt(3)
	v_mfma_f32_32x32x16_bf16 v[66:81], v[190:193], v[110:113], v[66:81]
	v_exp_f32_e32 v86, v85
	v_exp_f32_e32 v226, v88
	v_max_f32_e32 v85, v85, v88
	v_max3_f32 v0, v229, v0, v85
	v_add_f32_e32 v88, v86, v226
	v_add_f32_e32 v89, v87, v227
	v_cvt_pk_bf16_f32 v85, v86, v226
	v_add_f32_e32 v227, v88, v89
	ds_read_b128 v[86:89], v177 offset:8928
	s_waitcnt lgkmcnt(3)
	v_mfma_f32_32x32x16_bf16 v[66:81], v[194:197], v[114:117], v[66:81]
	s_waitcnt vmcnt(4)
	v_add_f32_e32 v90, v178, v90
	v_add_f32_e32 v91, v179, v91
	v_exp_f32_e32 v178, v91
	ds_read_b128 v[190:193], v228 offset:17408
	v_exp_f32_e32 v177, v90
	v_max_f32_e32 v91, v90, v91
	v_add_f32_e32 v179, v177, v178
	v_cvt_pk_bf16_f32 v90, v177, v178
	s_waitcnt lgkmcnt(3)
	v_mfma_f32_32x32x16_bf16 v[66:81], v[182:185], v[118:121], v[66:81]
	global_load_dwordx4 v[182:185], v[162:163], off offset:80
	v_add_f32_e32 v92, v180, v92
	v_add_f32_e32 v93, v181, v93
	v_exp_f32_e32 v178, v92
	v_exp_f32_e32 v226, v93
	v_max_f32_e32 v92, v92, v93
	v_max3_f32 v0, v0, v91, v92
	v_add_f32_e32 v92, v178, v226
	v_add_f32_e32 v93, v179, v227
	v_cvt_pk_bf16_f32 v91, v178, v226
	v_add_f32_e32 v227, v92, v93
	ds_read_b128 v[178:181], v228 offset:22016
	s_waitcnt lgkmcnt(3)
	v_mfma_f32_32x32x16_bf16 v[66:81], v[214:217], v[122:125], v[66:81]
	s_waitcnt vmcnt(4)
	v_add_f32_e32 v92, v198, v94
	v_add_f32_e32 v93, v199, v95
	v_exp_f32_e32 v94, v92
	v_exp_f32_e32 v177, v93
	v_max_f32_e32 v93, v92, v93
	v_add_f32_e32 v95, v94, v177
	v_cvt_pk_bf16_f32 v92, v94, v177
	ds_read_b128 v[194:197], v228 offset:26624
	s_waitcnt lgkmcnt(3)
	v_mfma_f32_32x32x16_bf16 v[66:81], v[86:89], v[126:129], v[66:81]
	v_add_f32_e32 v96, v200, v96
	v_add_f32_e32 v97, v201, v97
	v_exp_f32_e32 v94, v96
	v_exp_f32_e32 v226, v97
	v_max_f32_e32 v86, v96, v97
	v_max3_f32 v0, v0, v93, v86
	v_add_f32_e32 v86, v94, v226
	v_add_f32_e32 v87, v95, v227
	v_cvt_pk_bf16_f32 v93, v94, v226
	v_add_f32_e32 v199, v86, v87
	ds_read_b128 v[86:89], v228 offset:31232
	ds_read_b128 v[94:97], v228 offset:17440
	s_waitcnt lgkmcnt(4)
	v_mfma_f32_32x32x16_bf16 v[50:65], v[190:193], v[82:85], v[50:65]
	s_waitcnt vmcnt(3)
	v_add_f32_e32 v66, v218, v66
	v_add_f32_e32 v67, v219, v67
	v_exp_f32_e32 v177, v66
	v_exp_f32_e32 v190, v67
	v_max_f32_e32 v67, v66, v67
	v_add_f32_e32 v201, v177, v190
	v_cvt_pk_bf16_f32 v66, v177, v190
	ds_read_b128 v[190:193], v228 offset:22048
	s_waitcnt lgkmcnt(4)
	v_mfma_f32_32x32x16_bf16 v[34:49], v[178:181], v[82:85], v[34:49]
	v_add_f32_e32 v68, v220, v68
	v_add_f32_e32 v69, v221, v69
	v_exp_f32_e32 v198, v68
	v_exp_f32_e32 v200, v69
	v_max_f32_e32 v68, v68, v69
	v_max3_f32 v0, v0, v67, v68
	v_add_f32_e32 v68, v198, v200
	v_add_f32_e32 v69, v199, v201
	v_cvt_pk_bf16_f32 v67, v198, v200
	v_add_f32_e32 v199, v68, v69
	ds_read_b128 v[178:181], v228 offset:26656
	s_waitcnt lgkmcnt(4)
	v_mfma_f32_32x32x16_bf16 v[18:33], v[194:197], v[82:85], v[18:33]
	s_waitcnt vmcnt(2)
	v_add_f32_e32 v68, v202, v70
	v_add_f32_e32 v69, v203, v71
	v_exp_f32_e32 v70, v68
	v_exp_f32_e32 v177, v69
	v_max_f32_e32 v69, v68, v69
	v_add_f32_e32 v71, v70, v177
	v_cvt_pk_bf16_f32 v68, v70, v177
	ds_read_b128 v[194:197], v228 offset:31264
	s_waitcnt lgkmcnt(4)
	v_mfma_f32_32x32x16_bf16 v[2:17], v[86:89], v[82:85], v[2:17]
	v_add_f32_e32 v72, v204, v72
	v_add_f32_e32 v73, v205, v73
	v_exp_f32_e32 v70, v72
	v_exp_f32_e32 v198, v73
	v_max_f32_e32 v72, v72, v73
	v_max3_f32 v0, v0, v69, v72
	v_add_f32_e32 v72, v70, v198
	v_add_f32_e32 v73, v71, v199
	s_nop 0
	v_add_f32_e32 v73, v72, v73
	v_cvt_pk_bf16_f32 v69, v70, v198
	s_waitcnt lgkmcnt(3)
	v_mfma_f32_32x32x16_bf16 v[50:65], v[94:97], v[90:93], v[50:65]
	s_waitcnt vmcnt(1)
	v_add_f32_e32 v70, v186, v74
	v_add_f32_e32 v71, v187, v75
	v_exp_f32_e32 v72, v70
	v_exp_f32_e32 v74, v71
	v_max_f32_e32 v71, v70, v71
	v_add_f32_e32 v75, v72, v74
	v_cvt_pk_bf16_f32 v70, v72, v74
	v_add_f32_e32 v76, v188, v76
	v_add_f32_e32 v77, v189, v77
	v_exp_f32_e32 v74, v76
	v_exp_f32_e32 v72, v77
	v_max_f32_e32 v76, v76, v77
	v_max3_f32 v0, v0, v71, v76
	ds_read_b128 v[82:85], v228 offset:17472
	v_add_f32_e32 v76, v74, v72
	v_add_f32_e32 v77, v75, v73
	v_cvt_pk_bf16_f32 v71, v74, v72
	v_add_f32_e32 v95, v76, v77
	ds_read_b128 v[74:77], v228 offset:22080
	s_waitcnt lgkmcnt(4)
	v_mfma_f32_32x32x16_bf16 v[34:49], v[190:193], v[90:93], v[34:49]
	s_waitcnt lgkmcnt(0)
	v_mfma_f32_32x32x16_bf16 v[34:49], v[74:77], v[66:69], v[34:49]
	ds_read_b128 v[74:77], v228 offset:26720
	v_mfma_f32_32x32x16_bf16 v[18:33], v[178:181], v[90:93], v[18:33]
	s_waitcnt vmcnt(0)
	v_add_f32_e32 v72, v182, v78
	v_add_f32_e32 v73, v183, v79
	v_exp_f32_e32 v78, v72
	v_exp_f32_e32 v86, v73
	v_max_f32_e32 v177, v72, v73
	v_add_f32_e32 v79, v78, v86
	v_cvt_pk_bf16_f32 v72, v78, v86
	v_add_f32_e32 v73, v184, v80
	v_add_f32_e32 v80, v185, v81
	v_exp_f32_e32 v78, v73
	v_exp_f32_e32 v94, v80
	ds_read_b128 v[86:89], v228 offset:26688
	v_max_f32_e32 v178, v73, v80
	v_pk_add_f32 v[96:97], v[78:79], v[94:95]
	v_cvt_pk_bf16_f32 v73, v78, v94
	ds_read_b128 v[78:81], v228 offset:17504
	v_mfma_f32_32x32x16_bf16 v[50:65], v[82:85], v[66:69], v[50:65]
	ds_read_b128 v[82:85], v228 offset:31296
	v_mfma_f32_32x32x16_bf16 v[2:17], v[194:197], v[90:93], v[2:17]
	ds_read_b128 v[90:93], v228 offset:22112
	s_waitcnt lgkmcnt(3)
	v_mfma_f32_32x32x16_bf16 v[18:33], v[86:89], v[66:69], v[18:33]
	ds_read_b128 v[86:89], v228 offset:31328
	s_waitcnt lgkmcnt(2)
	v_mfma_f32_32x32x16_bf16 v[2:17], v[82:85], v[66:69], v[2:17]
	v_mfma_f32_32x32x16_bf16 v[50:65], v[78:81], v[70:73], v[50:65]
	s_waitcnt lgkmcnt(1)
	v_mfma_f32_32x32x16_bf16 v[34:49], v[90:93], v[70:73], v[34:49]
	v_mfma_f32_32x32x16_bf16 v[18:33], v[74:77], v[70:73], v[18:33]
	s_waitcnt lgkmcnt(0)
	v_mfma_f32_32x32x16_bf16 v[2:17], v[86:89], v[70:73], v[2:17]
	v_and_b32_e32 v67, 64, v210
	v_xor_b32_e32 v66, 32, v210
	v_add_u32_e32 v67, 64, v67
	v_cmp_lt_i32_e32 vcc, v66, v67
	v_max3_f32 v0, v0, v177, v178
	v_add_f32_e32 v67, v96, v97
	v_cndmask_b32_e32 v66, v210, v66, vcc
	v_lshlrev_b32_e32 v66, 2, v66
	ds_bpermute_b32 v66, v66, v0
	v_add_f32_e32 v168, v168, v67
	s_waitcnt lgkmcnt(0)
	v_max_f32_e32 v66, v66, v66
	v_max_f32_e32 v0, v0, v66
	v_cmp_lt_f32_e32 vcc, s87, v0
	s_cbranch_vccz .LBB0_46
	v_max_f32_e32 v0, v0, v0
	v_max_f32_e32 v66, 0, v0
	v_exp_f32_e64 v0, -v66
	v_add_f32_e32 v169, v169, v66
	v_xor_b32_e32 v230, 0x80000000, v169
	v_mov_b32_e32 v231, v230
	v_mov_b32_e32 v232, v230
	v_mov_b32_e32 v233, v230
	v_mov_b32_e32 v234, v230
	v_mov_b32_e32 v235, v230
	v_mov_b32_e32 v236, v230
	v_mov_b32_e32 v237, v230
	v_mov_b32_e32 v238, v230
	v_mov_b32_e32 v239, v230
	v_mov_b32_e32 v240, v230
	v_mov_b32_e32 v241, v230
	v_mov_b32_e32 v242, v230
	v_mov_b32_e32 v243, v230
	v_mov_b32_e32 v244, v230
	v_mov_b32_e32 v245, v230
	v_mul_f32_e32 v168, v168, v0
	v_pk_mul_f32 v[64:65], v[64:65], v[0:1] op_sel_hi:[1,0]
	v_pk_mul_f32 v[62:63], v[62:63], v[0:1] op_sel_hi:[1,0]
	v_pk_mul_f32 v[60:61], v[60:61], v[0:1] op_sel_hi:[1,0]
	v_pk_mul_f32 v[58:59], v[58:59], v[0:1] op_sel_hi:[1,0]
	v_pk_mul_f32 v[56:57], v[56:57], v[0:1] op_sel_hi:[1,0]
	v_pk_mul_f32 v[54:55], v[54:55], v[0:1] op_sel_hi:[1,0]
	v_pk_mul_f32 v[52:53], v[52:53], v[0:1] op_sel_hi:[1,0]
	v_pk_mul_f32 v[50:51], v[50:51], v[0:1] op_sel_hi:[1,0]
	v_pk_mul_f32 v[48:49], v[48:49], v[0:1] op_sel_hi:[1,0]
	v_pk_mul_f32 v[46:47], v[46:47], v[0:1] op_sel_hi:[1,0]
	v_pk_mul_f32 v[44:45], v[44:45], v[0:1] op_sel_hi:[1,0]
	v_pk_mul_f32 v[42:43], v[42:43], v[0:1] op_sel_hi:[1,0]
	v_pk_mul_f32 v[40:41], v[40:41], v[0:1] op_sel_hi:[1,0]
	v_pk_mul_f32 v[38:39], v[38:39], v[0:1] op_sel_hi:[1,0]
	v_pk_mul_f32 v[36:37], v[36:37], v[0:1] op_sel_hi:[1,0]
	v_pk_mul_f32 v[34:35], v[34:35], v[0:1] op_sel_hi:[1,0]
	v_pk_mul_f32 v[32:33], v[32:33], v[0:1] op_sel_hi:[1,0]
	v_pk_mul_f32 v[30:31], v[30:31], v[0:1] op_sel_hi:[1,0]
	v_pk_mul_f32 v[28:29], v[28:29], v[0:1] op_sel_hi:[1,0]
	v_pk_mul_f32 v[26:27], v[26:27], v[0:1] op_sel_hi:[1,0]
	v_pk_mul_f32 v[24:25], v[24:25], v[0:1] op_sel_hi:[1,0]
	v_pk_mul_f32 v[22:23], v[22:23], v[0:1] op_sel_hi:[1,0]
	v_pk_mul_f32 v[20:21], v[20:21], v[0:1] op_sel_hi:[1,0]
	v_pk_mul_f32 v[18:19], v[18:19], v[0:1] op_sel_hi:[1,0]
	v_pk_mul_f32 v[16:17], v[16:17], v[0:1] op_sel_hi:[1,0]
	v_pk_mul_f32 v[14:15], v[14:15], v[0:1] op_sel_hi:[1,0]
	v_pk_mul_f32 v[12:13], v[12:13], v[0:1] op_sel_hi:[1,0]
	v_pk_mul_f32 v[10:11], v[10:11], v[0:1] op_sel_hi:[1,0]
	v_pk_mul_f32 v[8:9], v[8:9], v[0:1] op_sel_hi:[1,0]
	v_pk_mul_f32 v[6:7], v[6:7], v[0:1] op_sel_hi:[1,0]
	v_pk_mul_f32 v[4:5], v[4:5], v[0:1] op_sel_hi:[1,0]
	v_pk_mul_f32 v[2:3], v[2:3], v[0:1] op_sel_hi:[1,0]

.LBB0_69:
	s_mul_i32 s30, s40, 0xac00
	s_add_i32 s30, s30, 0
	v_add_u32_e32 v188, s30, v165
	ds_read_b128 v[170:173], v188
	ds_read_b128 v[174:177], v188 offset:32
	ds_read_b128 v[178:181], v188 offset:64
	s_waitcnt lgkmcnt(2)
	v_mfma_f32_32x32x16_bf16 v[82:97], v[170:173], v[98:101], v[226:241]
	ds_read_b128 v[170:173], v188 offset:96
	s_waitcnt lgkmcnt(2)
	v_mfma_f32_32x32x16_bf16 v[82:97], v[174:177], v[102:105], v[82:97]
	ds_read_b128 v[174:177], v188 offset:128
	s_waitcnt lgkmcnt(2)
	v_mfma_f32_32x32x16_bf16 v[82:97], v[178:181], v[106:109], v[82:97]
	ds_read_b128 v[178:181], v188 offset:160
	s_waitcnt lgkmcnt(2)
	v_mfma_f32_32x32x16_bf16 v[82:97], v[170:173], v[110:113], v[82:97]
	ds_read_b128 v[170:173], v188 offset:192
	s_waitcnt lgkmcnt(2)
	v_mfma_f32_32x32x16_bf16 v[82:97], v[174:177], v[114:117], v[82:97]
	ds_read_b128 v[174:177], v188 offset:224
	s_waitcnt lgkmcnt(2)
	v_mfma_f32_32x32x16_bf16 v[82:97], v[178:181], v[118:121], v[82:97]
	ds_read_b128 v[178:181], v188 offset:8704
	s_waitcnt lgkmcnt(2)
	v_mfma_f32_32x32x16_bf16 v[82:97], v[170:173], v[122:125], v[82:97]
	ds_read_b128 v[170:173], v188 offset:8736
	s_waitcnt lgkmcnt(2)
	v_mfma_f32_32x32x16_bf16 v[82:97], v[174:177], v[126:129], v[82:97]
	ds_read_b128 v[174:177], v188 offset:8768
	v_add3_u32 v189, s30, v166, v164
	ds_read_b128 v[182:185], v188 offset:8800
	s_waitcnt lgkmcnt(3)
	v_mfma_f32_32x32x16_bf16 v[66:81], v[178:181], v[98:101], v[226:241]
	s_nop 6
	v_exp_f32_e32 v0, v82
	v_exp_f32_e32 v178, v83
	v_max_f32_e32 v83, v82, v83
	v_add_f32_e32 v187, v0, v178
	v_cvt_pk_bf16_f32 v82, v0, v178
	ds_read_b128 v[178:181], v188 offset:8832
	s_waitcnt lgkmcnt(3)
	v_mfma_f32_32x32x16_bf16 v[66:81], v[170:173], v[102:105], v[66:81]
	v_exp_f32_e32 v186, v84
	v_exp_f32_e32 v0, v85
	v_max_f32_e32 v84, v84, v85
	v_max3_f32 v190, v83, s86, v84
	v_add_f32_e32 v84, v186, v0
	v_add_f32_e32 v85, v187, v1
	v_cvt_pk_bf16_f32 v83, v186, v0
	v_add_f32_e32 v187, v84, v85
	ds_read_b128 v[170:173], v188 offset:8864
	s_waitcnt lgkmcnt(3)
	v_mfma_f32_32x32x16_bf16 v[66:81], v[174:177], v[106:109], v[66:81]
	v_exp_f32_e32 v84, v86
	v_exp_f32_e32 v85, v87
	v_max_f32_e32 v0, v86, v87
	v_add_f32_e32 v87, v84, v85
	v_cvt_pk_bf16_f32 v84, v84, v85
	ds_read_b128 v[174:177], v188 offset:8896
	s_waitcnt lgkmcnt(3)
	v_mfma_f32_32x32x16_bf16 v[66:81], v[182:185], v[110:113], v[66:81]
	v_exp_f32_e32 v86, v88
	v_exp_f32_e32 v186, v89
	v_max_f32_e32 v85, v88, v89
	v_add_f32_e32 v88, v86, v186
	v_add_f32_e32 v89, v87, v187
	v_max3_f32 v0, v190, v0, v85
	v_cvt_pk_bf16_f32 v85, v86, v186
	v_add_f32_e32 v187, v88, v89
	ds_read_b128 v[86:89], v188 offset:8928
	s_waitcnt lgkmcnt(3)
	v_mfma_f32_32x32x16_bf16 v[66:81], v[178:181], v[114:117], v[66:81]
	v_exp_f32_e32 v182, v90
	v_exp_f32_e32 v184, v91
	v_max_f32_e32 v91, v90, v91
	v_add_f32_e32 v183, v182, v184
	v_cvt_pk_bf16_f32 v90, v182, v184
	ds_read_b128 v[178:181], v189 offset:17408
	s_waitcnt lgkmcnt(3)
	v_mfma_f32_32x32x16_bf16 v[66:81], v[170:173], v[118:121], v[66:81]
	v_exp_f32_e32 v182, v92
	v_exp_f32_e32 v186, v93
	v_max_f32_e32 v92, v92, v93
	v_max3_f32 v0, v0, v91, v92
	v_add_f32_e32 v92, v182, v186
	v_add_f32_e32 v93, v183, v187
	v_cvt_pk_bf16_f32 v91, v182, v186
	v_add_f32_e32 v183, v92, v93
	ds_read_b128 v[170:173], v189 offset:22016
	s_waitcnt lgkmcnt(3)
	v_mfma_f32_32x32x16_bf16 v[66:81], v[174:177], v[122:125], v[66:81]
	v_exp_f32_e32 v93, v94
	v_exp_f32_e32 v182, v95
	v_max_f32_e32 v184, v94, v95
	v_add_f32_e32 v95, v93, v182
	v_cvt_pk_bf16_f32 v92, v93, v182
	ds_read_b128 v[174:177], v189 offset:26624
	s_waitcnt lgkmcnt(3)
	v_mfma_f32_32x32x16_bf16 v[66:81], v[86:89], v[126:129], v[66:81]
	v_exp_f32_e32 v94, v96
	v_exp_f32_e32 v182, v97
	v_max_f32_e32 v86, v96, v97
	v_max3_f32 v0, v0, v184, v86
	v_add_f32_e32 v86, v94, v182
	v_add_f32_e32 v87, v95, v183
	v_cvt_pk_bf16_f32 v93, v94, v182
	v_add_f32_e32 v183, v86, v87
	ds_read_b128 v[86:89], v189 offset:31232
	ds_read_b128 v[94:97], v189 offset:17440
	s_waitcnt lgkmcnt(4)
	v_mfma_f32_32x32x16_bf16 v[50:65], v[178:181], v[82:85], v[50:65]
	s_nop 0
	v_exp_f32_e32 v178, v66
	v_exp_f32_e32 v179, v67
	v_max_f32_e32 v67, v66, v67
	v_add_f32_e32 v185, v178, v179
	v_cvt_pk_bf16_f32 v66, v178, v179
	ds_read_b128 v[178:181], v189 offset:22048
	s_waitcnt lgkmcnt(4)
	v_mfma_f32_32x32x16_bf16 v[34:49], v[170:173], v[82:85], v[34:49]
	v_exp_f32_e32 v182, v68
	v_exp_f32_e32 v184, v69
	v_max_f32_e32 v68, v68, v69
	v_max3_f32 v0, v0, v67, v68
	v_add_f32_e32 v68, v182, v184
	v_add_f32_e32 v69, v183, v185
	v_cvt_pk_bf16_f32 v67, v182, v184
	v_add_f32_e32 v183, v68, v69
	ds_read_b128 v[170:173], v189 offset:26656
	s_waitcnt lgkmcnt(4)
	v_mfma_f32_32x32x16_bf16 v[18:33], v[174:177], v[82:85], v[18:33]
	v_exp_f32_e32 v68, v70
	v_exp_f32_e32 v69, v71
	v_max_f32_e32 v184, v70, v71
	v_add_f32_e32 v71, v68, v69
	v_cvt_pk_bf16_f32 v68, v68, v69
	ds_read_b128 v[174:177], v189 offset:31264
	s_waitcnt lgkmcnt(4)
	v_mfma_f32_32x32x16_bf16 v[2:17], v[86:89], v[82:85], v[2:17]
	v_exp_f32_e32 v70, v72
	v_exp_f32_e32 v182, v73
	v_max_f32_e32 v69, v72, v73
	v_add_f32_e32 v72, v70, v182
	v_add_f32_e32 v73, v71, v183
	v_max3_f32 v0, v0, v184, v69
	v_add_f32_e32 v73, v72, v73
	v_cvt_pk_bf16_f32 v69, v70, v182
	s_waitcnt lgkmcnt(3)
	v_mfma_f32_32x32x16_bf16 v[50:65], v[94:97], v[90:93], v[50:65]
	v_exp_f32_e32 v70, v74
	v_exp_f32_e32 v71, v75
	v_max_f32_e32 v86, v74, v75
	v_add_f32_e32 v75, v70, v71
	v_cvt_pk_bf16_f32 v70, v70, v71
	v_exp_f32_e32 v74, v76
	v_exp_f32_e32 v72, v77
	v_max_f32_e32 v71, v76, v77
	v_add_f32_e32 v76, v74, v72
	v_add_f32_e32 v77, v75, v73
	v_max3_f32 v0, v0, v86, v71
	v_add_f32_e32 v95, v76, v77
	v_cvt_pk_bf16_f32 v71, v74, v72
	ds_read_b128 v[74:77], v189 offset:22080
	s_waitcnt lgkmcnt(3)
	v_mfma_f32_32x32x16_bf16 v[34:49], v[178:181], v[90:93], v[34:49]
	ds_read_b128 v[82:85], v189 offset:17472
	s_waitcnt lgkmcnt(1)
	v_mfma_f32_32x32x16_bf16 v[34:49], v[74:77], v[66:69], v[34:49]
	ds_read_b128 v[74:77], v189 offset:26720
	v_mfma_f32_32x32x16_bf16 v[18:33], v[170:173], v[90:93], v[18:33]
	v_exp_f32_e32 v72, v78
	v_exp_f32_e32 v73, v79
	v_max_f32_e32 v170, v78, v79
	v_add_f32_e32 v79, v72, v73
	v_cvt_pk_bf16_f32 v72, v72, v73
	v_exp_f32_e32 v78, v80
	v_exp_f32_e32 v94, v81
	ds_read_b128 v[86:89], v189 offset:26688
	v_max_f32_e32 v171, v80, v81
	v_pk_add_f32 v[96:97], v[78:79], v[94:95]
	v_cvt_pk_bf16_f32 v73, v78, v94
	ds_read_b128 v[78:81], v189 offset:17504
	s_waitcnt lgkmcnt(3)
	v_mfma_f32_32x32x16_bf16 v[50:65], v[82:85], v[66:69], v[50:65]
	ds_read_b128 v[82:85], v189 offset:31296
	v_mfma_f32_32x32x16_bf16 v[2:17], v[174:177], v[90:93], v[2:17]
	ds_read_b128 v[90:93], v189 offset:22112
	s_waitcnt lgkmcnt(3)
	v_mfma_f32_32x32x16_bf16 v[18:33], v[86:89], v[66:69], v[18:33]
	ds_read_b128 v[86:89], v189 offset:31328
	v_max3_f32 v0, v0, v170, v171
	ds_bpermute_b32 v196, v167, v0
	v_add_f32_e32 v197, v96, v97
	v_add_f32_e32 v169, v169, v197
	s_xor_b32 s30, s40, 1
	s_mul_i32 s30, s30, 0xac00
	v_add_u32_e32 v192, s30, v148
	v_add3_u32 v193, s30, v149, v159
	v_add_u32_e32 v194, v192, v163
	v_add_u32_e32 v192, v192, v162
	v_add3_u32 v195, s30, v160, v161
	s_waitcnt vmcnt(3)
	ds_write_b128 v193, v[130:133]
	s_waitcnt vmcnt(2)
	ds_write_b128 v195, v[134:137]
	s_waitcnt vmcnt(1)
	ds_write_b128 v192, v[138:141] offset:17408
	s_waitcnt vmcnt(0)
	ds_write_b128 v194, v[142:145] offset:17408
	s_waitcnt lgkmcnt(7)
	v_mfma_f32_32x32x16_bf16 v[2:17], v[82:85], v[66:69], v[2:17]
	v_mfma_f32_32x32x16_bf16 v[50:65], v[78:81], v[70:73], v[50:65]
	s_waitcnt lgkmcnt(6)
	v_mfma_f32_32x32x16_bf16 v[34:49], v[90:93], v[70:73], v[34:49]
	v_mfma_f32_32x32x16_bf16 v[18:33], v[74:77], v[70:73], v[18:33]
	s_waitcnt lgkmcnt(5)
	v_mfma_f32_32x32x16_bf16 v[2:17], v[86:89], v[70:73], v[2:17]
	s_waitcnt lgkmcnt(0)
	v_max_f32_e32 v196, v196, v196
	v_max_f32_e32 v0, v0, v196
	v_cmp_lt_f32_e32 vcc, s87, v0
	s_cbranch_vccz .LBB0_71
	v_max_f32_e32 v0, v0, v0
	v_max_f32_e32 v66, 0, v0
	v_exp_f32_e64 v0, -v66
	v_add_f32_e32 v168, v168, v66
	v_xor_b32_e32 v226, 0x80000000, v168
	v_mov_b32_e32 v227, v226
	v_mov_b32_e32 v228, v226
	v_mov_b32_e32 v229, v226
	v_mov_b32_e32 v230, v226
	v_mov_b32_e32 v231, v226
	v_mov_b32_e32 v232, v226
	v_mov_b32_e32 v233, v226
	v_mov_b32_e32 v234, v226
	v_mov_b32_e32 v235, v226
	v_mov_b32_e32 v236, v226
	v_mov_b32_e32 v237, v226
	v_mov_b32_e32 v238, v226
	v_mov_b32_e32 v239, v226
	v_mov_b32_e32 v240, v226
	v_mov_b32_e32 v241, v226
	v_mul_f32_e32 v169, v169, v0
	v_pk_mul_f32 v[64:65], v[64:65], v[0:1] op_sel_hi:[1,0]
	v_pk_mul_f32 v[62:63], v[62:63], v[0:1] op_sel_hi:[1,0]
	v_pk_mul_f32 v[60:61], v[60:61], v[0:1] op_sel_hi:[1,0]
	v_pk_mul_f32 v[58:59], v[58:59], v[0:1] op_sel_hi:[1,0]
	v_pk_mul_f32 v[56:57], v[56:57], v[0:1] op_sel_hi:[1,0]
	v_pk_mul_f32 v[54:55], v[54:55], v[0:1] op_sel_hi:[1,0]
	v_pk_mul_f32 v[52:53], v[52:53], v[0:1] op_sel_hi:[1,0]
	v_pk_mul_f32 v[50:51], v[50:51], v[0:1] op_sel_hi:[1,0]
	v_pk_mul_f32 v[48:49], v[48:49], v[0:1] op_sel_hi:[1,0]
	v_pk_mul_f32 v[46:47], v[46:47], v[0:1] op_sel_hi:[1,0]
	v_pk_mul_f32 v[44:45], v[44:45], v[0:1] op_sel_hi:[1,0]
	v_pk_mul_f32 v[42:43], v[42:43], v[0:1] op_sel_hi:[1,0]
	v_pk_mul_f32 v[40:41], v[40:41], v[0:1] op_sel_hi:[1,0]
	v_pk_mul_f32 v[38:39], v[38:39], v[0:1] op_sel_hi:[1,0]
	v_pk_mul_f32 v[36:37], v[36:37], v[0:1] op_sel_hi:[1,0]
	v_pk_mul_f32 v[34:35], v[34:35], v[0:1] op_sel_hi:[1,0]
	v_pk_mul_f32 v[32:33], v[32:33], v[0:1] op_sel_hi:[1,0]
	v_pk_mul_f32 v[30:31], v[30:31], v[0:1] op_sel_hi:[1,0]
	v_pk_mul_f32 v[28:29], v[28:29], v[0:1] op_sel_hi:[1,0]
	v_pk_mul_f32 v[26:27], v[26:27], v[0:1] op_sel_hi:[1,0]
	v_pk_mul_f32 v[24:25], v[24:25], v[0:1] op_sel_hi:[1,0]
	v_pk_mul_f32 v[22:23], v[22:23], v[0:1] op_sel_hi:[1,0]
	v_pk_mul_f32 v[20:21], v[20:21], v[0:1] op_sel_hi:[1,0]
	v_pk_mul_f32 v[18:19], v[18:19], v[0:1] op_sel_hi:[1,0]
	v_pk_mul_f32 v[16:17], v[16:17], v[0:1] op_sel_hi:[1,0]
	v_pk_mul_f32 v[14:15], v[14:15], v[0:1] op_sel_hi:[1,0]
	v_pk_mul_f32 v[12:13], v[12:13], v[0:1] op_sel_hi:[1,0]
	v_pk_mul_f32 v[10:11], v[10:11], v[0:1] op_sel_hi:[1,0]
	v_pk_mul_f32 v[8:9], v[8:9], v[0:1] op_sel_hi:[1,0]
	v_pk_mul_f32 v[6:7], v[6:7], v[0:1] op_sel_hi:[1,0]
	v_pk_mul_f32 v[4:5], v[4:5], v[0:1] op_sel_hi:[1,0]
	v_pk_mul_f32 v[2:3], v[2:3], v[0:1] op_sel_hi:[1,0]

.LBB0_93:
	s_mul_i32 s0, s44, 0xac00
	s_sub_i32 s27, s45, 64
	s_add_i32 s48, s0, 0
	s_cmp_gt_i32 s27, s47
	s_cselect_b64 s[0:1], -1, 0
	s_cmp_lt_i32 s27, s46
	v_sub_f32_e32 v0, v230, v239
	s_cselect_b64 s[42:43], -1, 0
	v_cndmask_b32_e64 v66, v0, -v239, s[42:43]
	s_and_b64 s[42:43], s[0:1], s[42:43]
	s_andn2_b64 vcc, exec, s[42:43]
	v_add_u32_e32 v242, s48, v237
	v_add_u32_e32 v241, s48, v238
	s_cbranch_vccz .LBB0_95
	v_sub_f32_e32 v0, v229, v239
	ds_read_b128 v[100:103], v242
	ds_read_b128 v[104:107], v242 offset:32
	ds_read_b128 v[108:111], v242 offset:64
	v_cndmask_b32_e64 v68, v0, v66, s[0:1]
	v_mov_b32_e32 v69, v68
	v_mov_b32_e32 v70, v68
	v_mov_b32_e32 v71, v68
	v_mov_b32_e32 v72, v68
	v_mov_b32_e32 v73, v68
	v_mov_b32_e32 v74, v68
	v_mov_b32_e32 v75, v68
	v_mov_b32_e32 v76, v68
	v_mov_b32_e32 v77, v68
	v_mov_b32_e32 v78, v68
	v_mov_b32_e32 v79, v68
	v_mov_b32_e32 v80, v68
	v_mov_b32_e32 v81, v68
	v_mov_b32_e32 v82, v68
	v_mov_b32_e32 v83, v68
	ds_read_b128 v[112:115], v242 offset:96
	s_waitcnt lgkmcnt(3)
	v_mfma_f32_32x32x16_bf16 v[84:99], v[100:103], v[164:167], v[68:83]
	ds_read_b128 v[116:119], v242 offset:8704
	s_waitcnt lgkmcnt(3)
	v_mfma_f32_32x32x16_bf16 v[84:99], v[104:107], v[168:171], v[84:99]
	ds_read_b128 v[120:123], v242 offset:8736
	s_waitcnt lgkmcnt(3)
	v_mfma_f32_32x32x16_bf16 v[84:99], v[108:111], v[172:175], v[84:99]
	ds_read_b128 v[244:247], v241 offset:31232
	ds_read_b128 v[104:107], v242 offset:8768
	s_waitcnt lgkmcnt(4)
	v_mfma_f32_32x32x16_bf16 v[84:99], v[112:115], v[176:179], v[84:99]
	ds_read_b128 v[100:103], v242 offset:8800
	s_waitcnt lgkmcnt(4)
	v_mfma_f32_32x32x16_bf16 v[68:83], v[116:119], v[164:167], v[68:83]
	s_nop 8
	v_max_f32_e32 v0, v84, v85
	v_exp_f32_e32 v67, v84
	v_exp_f32_e32 v84, v85
	s_nop 0
	v_add_f32_e32 v85, v67, v84
	v_cvt_pk_bf16_f32 v180, v67, v84
	v_max_f32_e32 v67, v86, v87
	v_max3_f32 v67, v0, s86, v67
	v_exp_f32_e32 v84, v86
	v_exp_f32_e32 v0, v87
	s_nop 0
	v_add_f32_e32 v86, v84, v0
	v_add_f32_e32 v87, v85, v1
	s_nop 0
	v_add_f32_e32 v87, v86, v87
	v_cvt_pk_bf16_f32 v181, v84, v0
	ds_read_b128 v[108:111], v241 offset:17408
	v_max_f32_e32 v0, v88, v89
	v_exp_f32_e32 v84, v88
	v_exp_f32_e32 v86, v89
	s_waitcnt lgkmcnt(4)
	v_mfma_f32_32x32x16_bf16 v[68:83], v[120:123], v[168:171], v[68:83]
	v_add_f32_e32 v85, v84, v86
	v_cvt_pk_bf16_f32 v182, v84, v86
	v_max_f32_e32 v84, v90, v91
	v_max3_f32 v0, v67, v0, v84
	v_exp_f32_e32 v84, v90
	v_exp_f32_e32 v86, v91
	s_nop 0
	v_add_f32_e32 v88, v84, v86
	v_add_f32_e32 v89, v85, v87
	s_nop 0
	v_add_f32_e32 v89, v88, v89
	v_cvt_pk_bf16_f32 v183, v84, v86
	ds_read_b128 v[116:119], v241 offset:22016
	v_max_f32_e32 v67, v92, v93
	v_exp_f32_e32 v84, v92
	v_exp_f32_e32 v86, v93
	v_exp_f32_e32 v88, v95
	s_waitcnt lgkmcnt(3)
	v_mfma_f32_32x32x16_bf16 v[68:83], v[104:107], v[172:175], v[68:83]
	v_add_f32_e32 v85, v84, v86
	v_cvt_pk_bf16_f32 v184, v84, v86
	v_max_f32_e32 v84, v94, v95
	v_max3_f32 v0, v0, v67, v84
	v_exp_f32_e32 v84, v94
	s_nop 0
	v_add_f32_e32 v86, v84, v88
	v_add_f32_e32 v87, v85, v89
	s_nop 0
	v_add_f32_e32 v87, v86, v87
	v_cvt_pk_bf16_f32 v185, v84, v88
	ds_read_b128 v[132:135], v241 offset:26624
	v_max_f32_e32 v67, v96, v97
	v_exp_f32_e32 v84, v96
	v_exp_f32_e32 v86, v97
	s_waitcnt lgkmcnt(3)
	v_mfma_f32_32x32x16_bf16 v[68:83], v[100:103], v[176:179], v[68:83]
	v_add_f32_e32 v85, v84, v86
	v_cvt_pk_bf16_f32 v186, v84, v86
	v_max_f32_e32 v84, v98, v99
	v_max3_f32 v0, v0, v67, v84
	v_exp_f32_e32 v84, v98
	v_exp_f32_e32 v86, v99
	s_nop 0
	v_add_f32_e32 v88, v84, v86
	v_add_f32_e32 v89, v85, v87
	s_nop 0
	v_add_f32_e32 v121, v88, v89
	v_cvt_pk_bf16_f32 v187, v84, v86
	ds_read_b128 v[188:191], v241 offset:17440
	s_waitcnt lgkmcnt(3)
	v_mfma_f32_32x32x16_bf16 v[34:49], v[108:111], v[180:183], v[34:49]
	v_max_f32_e32 v67, v69, v69
	v_max_f32_e32 v100, v68, v68
	v_exp_f32_e32 v68, v68
	v_exp_f32_e32 v69, v69
	v_max_f32_e32 v67, v100, v67
	v_add_f32_e32 v123, v68, v69
	v_cvt_pk_bf16_f32 v68, v68, v69
	ds_read_b128 v[214:217], v241 offset:22048
	s_waitcnt lgkmcnt(3)
	v_mfma_f32_32x32x16_bf16 v[18:33], v[116:119], v[180:183], v[18:33]
	v_exp_f32_e32 v120, v70
	v_exp_f32_e32 v122, v71
	v_max_f32_e32 v69, v70, v71
	v_add_f32_e32 v70, v120, v122
	v_add_f32_e32 v71, v121, v123
	v_max3_f32 v0, v0, v67, v69
	v_add_f32_e32 v249, v70, v71
	v_cvt_pk_bf16_f32 v69, v120, v122
	ds_read_b128 v[218:221], v241 offset:26656
	s_waitcnt lgkmcnt(3)
	v_mfma_f32_32x32x16_bf16 v[2:17], v[132:135], v[180:183], v[2:17]
	v_max_f32_e32 v67, v72, v73
	v_exp_f32_e32 v70, v72
	v_exp_f32_e32 v71, v73
	s_nop 0
	v_add_f32_e32 v73, v70, v71
	v_cvt_pk_bf16_f32 v70, v70, v71
	v_mfma_f32_32x32x16_bf16 v[50:65], v[244:247], v[180:183], v[50:65]
	v_max_f32_e32 v71, v74, v75
	v_exp_f32_e32 v72, v74
	v_exp_f32_e32 v248, v75
	v_max3_f32 v0, v0, v67, v71
	v_add_f32_e32 v74, v72, v248
	v_add_f32_e32 v75, v73, v249
	s_nop 0
	v_add_f32_e32 v245, v74, v75
	v_cvt_pk_bf16_f32 v71, v72, v248
	ds_read_b128 v[72:75], v241 offset:31264
	s_waitcnt lgkmcnt(3)
	v_mfma_f32_32x32x16_bf16 v[34:49], v[188:191], v[184:187], v[34:49]
	v_max_f32_e32 v67, v77, v77
	v_max_f32_e32 v180, v76, v76
	v_exp_f32_e32 v76, v76
	v_exp_f32_e32 v77, v77
	v_max_f32_e32 v67, v180, v67
	v_add_f32_e32 v189, v76, v77
	v_cvt_pk_bf16_f32 v76, v76, v77
	ds_read_b128 v[180:183], v241 offset:17472
	s_waitcnt lgkmcnt(3)
	v_mfma_f32_32x32x16_bf16 v[18:33], v[214:217], v[184:187], v[18:33]
	v_max_f32_e32 v77, v78, v79
	v_exp_f32_e32 v188, v78
	v_exp_f32_e32 v244, v79
	v_max3_f32 v0, v0, v67, v77
	v_add_f32_e32 v78, v188, v244
	v_add_f32_e32 v79, v189, v245
	s_nop 0
	v_add_f32_e32 v247, v78, v79
	v_cvt_pk_bf16_f32 v77, v188, v244
	ds_read_b128 v[188:191], v241 offset:22080
	s_waitcnt lgkmcnt(3)
	v_mfma_f32_32x32x16_bf16 v[2:17], v[218:221], v[184:187], v[2:17]
	v_max_f32_e32 v67, v80, v81
	v_exp_f32_e32 v78, v80
	v_exp_f32_e32 v79, v81
	s_nop 0
	v_add_f32_e32 v81, v78, v79
	v_cvt_pk_bf16_f32 v78, v78, v79
	ds_read_b128 v[214:217], v241 offset:26688
	s_waitcnt lgkmcnt(3)
	v_mfma_f32_32x32x16_bf16 v[50:65], v[72:75], v[184:187], v[50:65]
	v_exp_f32_e32 v80, v82
	v_exp_f32_e32 v246, v83
	v_max_f32_e32 v220, v82, v83
	v_pk_add_f32 v[218:219], v[80:81], v[246:247]
	v_cvt_pk_bf16_f32 v79, v80, v246
	ds_read_b128 v[72:75], v241 offset:31296
	ds_read_b128 v[80:83], v241 offset:17504
	s_waitcnt lgkmcnt(4)
	v_mfma_f32_32x32x16_bf16 v[34:49], v[180:183], v[68:71], v[34:49]
	ds_read_b128 v[180:183], v241 offset:22112
	s_waitcnt lgkmcnt(4)
	v_mfma_f32_32x32x16_bf16 v[18:33], v[188:191], v[68:71], v[18:33]
	ds_read_b128 v[184:187], v241 offset:26720
	s_waitcnt lgkmcnt(4)
	v_mfma_f32_32x32x16_bf16 v[2:17], v[214:217], v[68:71], v[2:17]
	s_waitcnt lgkmcnt(3)
	v_mfma_f32_32x32x16_bf16 v[50:65], v[72:75], v[68:71], v[50:65]
	ds_read_b128 v[68:71], v241 offset:31328
	s_waitcnt lgkmcnt(3)
	v_mfma_f32_32x32x16_bf16 v[34:49], v[80:83], v[76:79], v[34:49]
	s_waitcnt lgkmcnt(2)
	v_mfma_f32_32x32x16_bf16 v[18:33], v[180:183], v[76:79], v[18:33]
	s_waitcnt lgkmcnt(1)
	v_mfma_f32_32x32x16_bf16 v[2:17], v[184:187], v[76:79], v[2:17]
	s_waitcnt lgkmcnt(0)
	v_mfma_f32_32x32x16_bf16 v[50:65], v[68:71], v[76:79], v[50:65]
	v_max3_f32 v67, v0, v67, v220
	ds_bpermute_b32 v68, v195, v67
	v_add_f32_e32 v0, v218, v219
	v_add_f32_e32 v0, v240, v0
	s_waitcnt lgkmcnt(0)
	v_max_f32_e32 v68, v68, v68
	v_max_f32_e32 v67, v67, v68
	v_cmp_lt_f32_e32 vcc, s87, v67
	s_cmp_lg_u64 vcc, 0
	s_cselect_b64 s[0:1], -1, 0
	s_cbranch_execz .LBB0_96
	s_branch .LBB0_97

.LBB0_96:
	v_lshl_add_u64 v[138:139], s[88:89], 0, v[204:205]
	ds_read_b128 v[98:101], v242
	ds_read_b128 v[102:105], v242 offset:32
	ds_read_b128 v[106:109], v242 offset:64
	global_load_dwordx4 v[110:113], v[138:139], off offset:-128
	global_load_dwordx4 v[114:117], v[138:139], off offset:-112
	v_mov_b32_e32 v67, v66
	v_mov_b32_e32 v68, v66
	v_mov_b32_e32 v69, v66
	v_mov_b32_e32 v70, v66
	v_mov_b32_e32 v71, v66
	v_mov_b32_e32 v72, v66
	v_mov_b32_e32 v73, v66
	v_mov_b32_e32 v74, v66
	v_mov_b32_e32 v75, v66
	v_mov_b32_e32 v76, v66
	v_mov_b32_e32 v77, v66
	v_mov_b32_e32 v78, v66
	v_mov_b32_e32 v79, v66
	v_mov_b32_e32 v80, v66
	v_mov_b32_e32 v81, v66
	global_load_dwordx4 v[122:125], v[138:139], off offset:-64
	s_waitcnt lgkmcnt(2)
	v_mfma_f32_32x32x16_bf16 v[82:97], v[98:101], v[164:167], v[66:81]
	ds_read_b128 v[98:101], v242 offset:96
	ds_read_b128 v[118:121], v242 offset:8704
	s_waitcnt lgkmcnt(3)
	v_mfma_f32_32x32x16_bf16 v[82:97], v[102:105], v[168:171], v[82:97]
	ds_read_b128 v[126:129], v242 offset:8736
	s_waitcnt lgkmcnt(3)
	v_mfma_f32_32x32x16_bf16 v[82:97], v[106:109], v[172:175], v[82:97]
	s_waitcnt lgkmcnt(2)
	v_mfma_f32_32x32x16_bf16 v[82:97], v[98:101], v[176:179], v[82:97]
	global_load_dwordx4 v[130:133], v[138:139], off offset:-48
	global_load_dwordx4 v[134:137], v[138:139], off
	global_load_dwordx4 v[106:109], v[138:139], off offset:16
	global_load_dwordx4 v[98:101], v[138:139], off offset:80
	global_load_dwordx4 v[102:105], v[138:139], off offset:64
	ds_read_b128 v[138:141], v242 offset:8768
	ds_read_b128 v[142:145], v242 offset:8800
	s_waitcnt vmcnt(7)
	s_nop 3
	v_add_f32_e32 v0, v110, v82
	v_add_f32_e32 v82, v111, v83
	v_add_f32_e32 v83, v112, v84
	v_add_f32_e32 v85, v113, v85
	v_max_f32_e32 v110, v0, v82
	v_exp_f32_e32 v111, v0
	v_exp_f32_e32 v82, v82
	v_exp_f32_e32 v84, v83
	v_exp_f32_e32 v0, v85
	s_waitcnt lgkmcnt(3)
	v_mfma_f32_32x32x16_bf16 v[66:81], v[118:121], v[164:167], v[66:81]
	v_max_f32_e32 v112, v83, v85
	v_add_f32_e32 v85, v111, v82
	v_cvt_pk_bf16_f32 v83, v84, v0
	v_add_f32_e64 v84, v84, v0
	v_add_f32_e64 v85, v85, v1
	v_max3_f32 v120, v110, s86, v112
	v_cvt_pk_bf16_f32 v82, v111, v82
	v_pk_add_f32 v[118:119], v[84:85], v[84:85] op_sel_hi:[0,1]
	ds_read_b128 v[110:113], v241 offset:17408
	s_waitcnt vmcnt(6)
	v_add_f32_e32 v0, v114, v86
	v_add_f32_e32 v84, v115, v87
	v_add_f32_e32 v85, v116, v88
	v_add_f32_e32 v87, v117, v89
	v_max_f32_e32 v88, v0, v84
	v_exp_f32_e32 v0, v0
	v_exp_f32_e32 v84, v84
	v_exp_f32_e32 v86, v85
	v_exp_f32_e32 v118, v87
	s_waitcnt lgkmcnt(3)
	v_mfma_f32_32x32x16_bf16 v[66:81], v[126:129], v[168:171], v[66:81]
	v_max_f32_e32 v89, v85, v87
	v_add_f32_e32 v87, v0, v84
	v_cvt_pk_bf16_f32 v85, v86, v118
	v_add_f32_e64 v86, v86, v118
	v_add_f32_e64 v87, v87, v119
	v_max3_f32 v116, v120, v88, v89
	v_cvt_pk_bf16_f32 v84, v0, v84
	v_pk_add_f32 v[114:115], v[86:87], v[86:87] op_sel_hi:[0,1]
	ds_read_b128 v[86:89], v241 offset:22016
	s_waitcnt vmcnt(5)
	v_add_f32_e32 v0, v122, v90
	v_add_f32_e32 v90, v123, v91
	v_add_f32_e32 v91, v124, v92
	v_add_f32_e32 v93, v125, v93
	v_max_f32_e32 v117, v0, v90
	v_exp_f32_e32 v0, v0
	v_exp_f32_e32 v90, v90
	v_exp_f32_e32 v92, v91
	v_exp_f32_e32 v114, v93
	v_max_f32_e32 v118, v91, v93
	v_add_f32_e32 v93, v0, v90
	v_max3_f32 v120, v116, v117, v118
	v_cvt_pk_bf16_f32 v91, v92, v114
	v_pk_add_f32 v[92:93], v[92:93], v[114:115]
	ds_read_b128 v[114:117], v241 offset:26624
	s_waitcnt lgkmcnt(4)
	v_mfma_f32_32x32x16_bf16 v[66:81], v[138:141], v[172:175], v[66:81]
	v_cvt_pk_bf16_f32 v90, v0, v90
	v_add_f32_e64 v118, v92, v92
	v_add_f32_e64 v119, v92, v93
	s_waitcnt vmcnt(4)
	v_add_f32_e32 v0, v130, v94
	v_add_f32_e32 v92, v131, v95
	v_add_f32_e32 v93, v132, v96
	v_add_f32_e32 v95, v133, v97
	v_max_f32_e32 v96, v0, v92
	s_waitcnt lgkmcnt(3)
	v_mfma_f32_32x32x16_bf16 v[66:81], v[142:145], v[176:179], v[66:81]
	v_exp_f32_e32 v0, v0
	v_exp_f32_e32 v92, v92
	v_exp_f32_e32 v94, v93
	v_exp_f32_e32 v118, v95
	v_max_f32_e32 v97, v93, v95
	v_add_f32_e32 v95, v0, v92
	v_max3_f32 v126, v120, v96, v97
	v_cvt_pk_bf16_f32 v93, v94, v118
	v_add_f32_e32 v94, v94, v118
	v_add_f32_e32 v95, v95, v119
	v_cvt_pk_bf16_f32 v92, v0, v92
	v_add_f32_e32 v123, v94, v95
	ds_read_b128 v[94:97], v241 offset:31232
	ds_read_b128 v[118:121], v241 offset:17440
	s_waitcnt lgkmcnt(4)
	v_mfma_f32_32x32x16_bf16 v[34:49], v[110:113], v[82:85], v[34:49]
	s_waitcnt vmcnt(3)
	v_add_f32_e32 v0, v134, v66
	v_add_f32_e32 v66, v135, v67
	v_exp_f32_e32 v67, v0
	v_exp_f32_e32 v110, v66
	v_max_f32_e32 v0, v0, v66
	v_add_f32_e32 v125, v67, v110
	v_cvt_pk_bf16_f32 v66, v67, v110
	ds_read_b128 v[110:113], v241 offset:22048
	s_waitcnt lgkmcnt(4)
	v_mfma_f32_32x32x16_bf16 v[18:33], v[86:89], v[82:85], v[18:33]
	v_add_f32_e32 v67, v136, v68
	v_add_f32_e32 v68, v137, v69
	v_exp_f32_e32 v122, v67
	v_exp_f32_e32 v124, v68
	v_max_f32_e32 v67, v67, v68
	v_max3_f32 v0, v126, v0, v67
	v_add_f32_e32 v68, v122, v124
	v_add_f32_e32 v69, v123, v125
	s_nop 0
	v_add_f32_e32 v127, v68, v69
	v_cvt_pk_bf16_f32 v67, v122, v124
	ds_read_b128 v[86:89], v241 offset:26656
	s_waitcnt lgkmcnt(4)
	v_mfma_f32_32x32x16_bf16 v[2:17], v[114:117], v[82:85], v[2:17]
	s_waitcnt vmcnt(2)
	v_add_f32_e32 v68, v106, v70
	v_add_f32_e32 v69, v107, v71
	v_exp_f32_e32 v70, v68
	v_exp_f32_e32 v106, v69
	v_max_f32_e32 v69, v68, v69
	v_add_f32_e32 v71, v70, v106
	v_cvt_pk_bf16_f32 v68, v70, v106
	ds_read_b128 v[114:117], v241 offset:31264
	s_waitcnt lgkmcnt(4)
	v_mfma_f32_32x32x16_bf16 v[50:65], v[94:97], v[82:85], v[50:65]
	v_add_f32_e32 v72, v108, v72
	v_add_f32_e32 v73, v109, v73
	v_exp_f32_e32 v70, v72
	v_exp_f32_e32 v126, v73
	v_max_f32_e32 v72, v72, v73
	v_max3_f32 v0, v0, v69, v72
	v_add_f32_e32 v72, v70, v126
	v_add_f32_e32 v73, v71, v127
	s_nop 0
	v_add_f32_e32 v73, v72, v73
	v_cvt_pk_bf16_f32 v69, v70, v126
	s_waitcnt lgkmcnt(3)
	v_mfma_f32_32x32x16_bf16 v[34:49], v[118:121], v[90:93], v[34:49]
	s_waitcnt vmcnt(0)
	v_add_f32_e32 v70, v102, v74
	v_add_f32_e32 v71, v103, v75
	v_exp_f32_e32 v72, v70
	v_exp_f32_e32 v74, v71
	v_max_f32_e32 v71, v70, v71
	v_add_f32_e32 v75, v72, v74
	v_cvt_pk_bf16_f32 v70, v72, v74
	v_add_f32_e32 v76, v104, v76
	v_add_f32_e32 v77, v105, v77
	v_exp_f32_e32 v74, v76
	v_exp_f32_e32 v72, v77
	v_max_f32_e32 v76, v76, v77
	v_max3_f32 v0, v0, v71, v76
	ds_read_b128 v[82:85], v241 offset:17472
	v_add_f32_e32 v76, v74, v72
	v_add_f32_e32 v77, v75, v73
	v_cvt_pk_bf16_f32 v71, v74, v72
	v_add_f32_e32 v95, v76, v77
	ds_read_b128 v[74:77], v241 offset:22080
	s_waitcnt lgkmcnt(4)
	v_mfma_f32_32x32x16_bf16 v[18:33], v[110:113], v[90:93], v[18:33]
	s_waitcnt lgkmcnt(0)
	v_mfma_f32_32x32x16_bf16 v[18:33], v[74:77], v[66:69], v[18:33]
	ds_read_b128 v[74:77], v241 offset:26720
	v_mfma_f32_32x32x16_bf16 v[2:17], v[86:89], v[90:93], v[2:17]
	v_add_f32_e32 v72, v98, v78
	v_add_f32_e32 v73, v99, v79
	v_exp_f32_e32 v78, v72
	v_exp_f32_e32 v86, v73
	v_max_f32_e32 v98, v72, v73
	v_add_f32_e32 v79, v78, v86
	v_cvt_pk_bf16_f32 v72, v78, v86
	v_add_f32_e32 v73, v100, v80
	v_add_f32_e32 v80, v101, v81
	v_exp_f32_e32 v78, v73
	v_exp_f32_e32 v94, v80
	ds_read_b128 v[86:89], v241 offset:26688
	v_max_f32_e32 v99, v73, v80
	v_pk_add_f32 v[96:97], v[78:79], v[94:95]
	v_cvt_pk_bf16_f32 v73, v78, v94
	ds_read_b128 v[78:81], v241 offset:17504
	v_mfma_f32_32x32x16_bf16 v[34:49], v[82:85], v[66:69], v[34:49]
	ds_read_b128 v[82:85], v241 offset:31296
	v_mfma_f32_32x32x16_bf16 v[50:65], v[114:117], v[90:93], v[50:65]
	ds_read_b128 v[90:93], v241 offset:22112
	s_waitcnt lgkmcnt(3)
	v_mfma_f32_32x32x16_bf16 v[2:17], v[86:89], v[66:69], v[2:17]
	ds_read_b128 v[86:89], v241 offset:31328
	s_waitcnt lgkmcnt(2)
	v_mfma_f32_32x32x16_bf16 v[50:65], v[82:85], v[66:69], v[50:65]
	v_mfma_f32_32x32x16_bf16 v[34:49], v[78:81], v[70:73], v[34:49]
	s_waitcnt lgkmcnt(1)
	v_mfma_f32_32x32x16_bf16 v[18:33], v[90:93], v[70:73], v[18:33]
	v_mfma_f32_32x32x16_bf16 v[2:17], v[74:77], v[70:73], v[2:17]
	s_waitcnt lgkmcnt(0)
	v_mfma_f32_32x32x16_bf16 v[50:65], v[86:89], v[70:73], v[50:65]
	v_max3_f32 v66, v0, v98, v99
	ds_bpermute_b32 v67, v195, v66
	v_add_f32_e32 v0, v96, v97
	s_nop 3
	s_nop 0
	s_waitcnt lgkmcnt(0)
	v_max_f32_e32 v67, v67, v67
	v_max_f32_e32 v67, v66, v67
	v_cmp_lt_f32_e32 vcc, s87, v67
	s_cmp_lg_u64 vcc, 0
	v_add_f32_e32 v0, v240, v0
	s_cselect_b64 s[0:1], -1, 0

.LBB0_111:
	s_mul_i32 s28, s40, 0xac00
	s_add_i32 s28, s28, 0
	v_add_u32_e32 v220, s28, v189
	ds_read_b128 v[194:197], v220
	ds_read_b128 v[198:201], v220 offset:32
	ds_read_b128 v[202:205], v220 offset:64
	s_waitcnt lgkmcnt(2)
	v_mfma_f32_32x32x16_bf16 v[82:97], v[194:197], v[98:101], v[228:243]
	ds_read_b128 v[194:197], v220 offset:96
	s_waitcnt lgkmcnt(2)
	v_mfma_f32_32x32x16_bf16 v[82:97], v[198:201], v[102:105], v[82:97]
	ds_read_b128 v[198:201], v220 offset:128
	s_waitcnt lgkmcnt(2)
	v_mfma_f32_32x32x16_bf16 v[82:97], v[202:205], v[106:109], v[82:97]
	ds_read_b128 v[202:205], v220 offset:160
	s_waitcnt lgkmcnt(2)
	v_mfma_f32_32x32x16_bf16 v[82:97], v[194:197], v[110:113], v[82:97]
	ds_read_b128 v[194:197], v220 offset:192
	s_waitcnt lgkmcnt(2)
	v_mfma_f32_32x32x16_bf16 v[82:97], v[198:201], v[114:117], v[82:97]
	ds_read_b128 v[198:201], v220 offset:224
	s_waitcnt lgkmcnt(2)
	v_mfma_f32_32x32x16_bf16 v[82:97], v[202:205], v[118:121], v[82:97]
	ds_read_b128 v[202:205], v220 offset:256
	s_waitcnt lgkmcnt(2)
	v_mfma_f32_32x32x16_bf16 v[82:97], v[194:197], v[122:125], v[82:97]
	ds_read_b128 v[194:197], v220 offset:288
	s_waitcnt lgkmcnt(2)
	v_mfma_f32_32x32x16_bf16 v[82:97], v[198:201], v[126:129], v[82:97]
	ds_read_b128 v[198:201], v220 offset:320
	s_waitcnt lgkmcnt(2)
	v_mfma_f32_32x32x16_bf16 v[82:97], v[202:205], v[130:133], v[82:97]
	ds_read_b128 v[202:205], v220 offset:352
	s_waitcnt lgkmcnt(2)
	v_mfma_f32_32x32x16_bf16 v[82:97], v[194:197], v[134:137], v[82:97]
	ds_read_b128 v[194:197], v220 offset:12800
	s_waitcnt lgkmcnt(2)
	v_mfma_f32_32x32x16_bf16 v[82:97], v[198:201], v[138:141], v[82:97]
	ds_read_b128 v[198:201], v220 offset:12832
	s_waitcnt lgkmcnt(2)
	v_mfma_f32_32x32x16_bf16 v[82:97], v[202:205], v[142:145], v[82:97]
	ds_read_b128 v[202:205], v220 offset:12864
	v_add3_u32 v221, s28, v190, v188
	s_waitcnt lgkmcnt(2)
	v_mfma_f32_32x32x16_bf16 v[66:81], v[194:197], v[98:101], v[228:243]
	ds_read_b128 v[194:197], v220 offset:12896
	ds_read_b128 v[214:217], v220 offset:12928
	s_waitcnt lgkmcnt(3)
	v_mfma_f32_32x32x16_bf16 v[66:81], v[198:201], v[102:105], v[66:81]
	s_nop 3
	v_exp_f32_e32 v0, v82
	v_exp_f32_e32 v198, v83
	v_max_f32_e32 v83, v82, v83
	v_add_f32_e32 v219, v0, v198
	v_cvt_pk_bf16_f32 v82, v0, v198
	s_waitcnt lgkmcnt(2)
	v_mfma_f32_32x32x16_bf16 v[66:81], v[202:205], v[106:109], v[66:81]
	ds_read_b128 v[198:201], v220 offset:12960
	v_exp_f32_e32 v218, v84
	v_exp_f32_e32 v0, v85
	v_max_f32_e32 v84, v84, v85
	v_max3_f32 v226, v83, s86, v84
	v_add_f32_e32 v84, v218, v0
	v_add_f32_e32 v85, v219, v1
	v_cvt_pk_bf16_f32 v83, v218, v0
	v_add_f32_e32 v219, v84, v85
	s_waitcnt lgkmcnt(2)
	v_mfma_f32_32x32x16_bf16 v[66:81], v[194:197], v[110:113], v[66:81]
	ds_read_b128 v[194:197], v220 offset:12992
	ds_read_b128 v[202:205], v220 offset:13024
	s_waitcnt lgkmcnt(3)
	v_mfma_f32_32x32x16_bf16 v[66:81], v[214:217], v[114:117], v[66:81]
	v_exp_f32_e32 v0, v86
	v_exp_f32_e32 v84, v87
	v_max_f32_e32 v85, v86, v87
	v_add_f32_e32 v87, v0, v84
	v_cvt_pk_bf16_f32 v84, v0, v84
	s_waitcnt lgkmcnt(2)
	v_mfma_f32_32x32x16_bf16 v[66:81], v[198:201], v[118:121], v[66:81]
	ds_read_b128 v[214:217], v220 offset:13056
	v_exp_f32_e32 v86, v88
	v_exp_f32_e32 v218, v89
	v_max_f32_e32 v0, v88, v89
	v_add_f32_e32 v88, v86, v218
	v_add_f32_e32 v89, v87, v219
	v_max3_f32 v0, v226, v85, v0
	v_cvt_pk_bf16_f32 v85, v86, v218
	v_add_f32_e32 v219, v88, v89
	s_waitcnt lgkmcnt(2)
	v_mfma_f32_32x32x16_bf16 v[66:81], v[194:197], v[122:125], v[66:81]
	ds_read_b128 v[86:89], v220 offset:13088
	ds_read_b128 v[194:197], v220 offset:13120
	s_waitcnt lgkmcnt(3)
	v_mfma_f32_32x32x16_bf16 v[66:81], v[202:205], v[126:129], v[66:81]
	v_exp_f32_e32 v198, v90
	v_exp_f32_e32 v199, v91
	v_max_f32_e32 v91, v90, v91
	v_add_f32_e32 v203, v198, v199
	v_cvt_pk_bf16_f32 v90, v198, v199
	s_waitcnt lgkmcnt(2)
	v_mfma_f32_32x32x16_bf16 v[66:81], v[214:217], v[130:133], v[66:81]
	ds_read_b128 v[198:201], v220 offset:13152
	v_exp_f32_e32 v202, v92
	v_exp_f32_e32 v218, v93
	v_max_f32_e32 v92, v92, v93
	v_max3_f32 v0, v0, v91, v92
	v_add_f32_e32 v92, v202, v218
	v_add_f32_e32 v93, v203, v219
	v_cvt_pk_bf16_f32 v91, v202, v218
	v_add_f32_e32 v215, v92, v93
	s_waitcnt lgkmcnt(2)
	v_mfma_f32_32x32x16_bf16 v[66:81], v[86:89], v[134:137], v[66:81]
	ds_read_b128 v[86:89], v221 offset:25600
	ds_read_b128 v[202:205], v221 offset:30208
	s_waitcnt lgkmcnt(3)
	v_mfma_f32_32x32x16_bf16 v[66:81], v[194:197], v[138:141], v[66:81]
	v_exp_f32_e32 v92, v94
	v_exp_f32_e32 v93, v95
	v_max_f32_e32 v216, v94, v95
	v_add_f32_e32 v95, v92, v93
	v_cvt_pk_bf16_f32 v92, v92, v93
	ds_read_b128 v[194:197], v221 offset:34816
	s_waitcnt lgkmcnt(3)
	v_mfma_f32_32x32x16_bf16 v[66:81], v[198:201], v[142:145], v[66:81]
	v_exp_f32_e32 v94, v96
	v_exp_f32_e32 v214, v97
	v_max_f32_e32 v93, v96, v97
	v_add_f32_e32 v96, v94, v214
	v_add_f32_e32 v97, v95, v215
	v_max3_f32 v0, v0, v216, v93
	v_cvt_pk_bf16_f32 v93, v94, v214
	v_add_f32_e32 v215, v96, v97
	ds_read_b128 v[94:97], v221 offset:39424
	ds_read_b128 v[198:201], v221 offset:25632
	s_waitcnt lgkmcnt(4)
	v_mfma_f32_32x32x16_bf16 v[2:17], v[86:89], v[82:85], v[2:17]
	s_nop 0
	v_exp_f32_e32 v86, v66
	v_exp_f32_e32 v87, v67
	v_max_f32_e32 v67, v66, v67
	v_add_f32_e32 v217, v86, v87
	v_cvt_pk_bf16_f32 v66, v86, v87
	ds_read_b128 v[86:89], v221 offset:30240
	s_waitcnt lgkmcnt(4)
	v_mfma_f32_32x32x16_bf16 v[50:65], v[202:205], v[82:85], v[50:65]
	v_exp_f32_e32 v214, v68
	v_exp_f32_e32 v216, v69
	v_max_f32_e32 v68, v68, v69
	v_max3_f32 v0, v0, v67, v68
	v_add_f32_e32 v68, v214, v216
	v_add_f32_e32 v69, v215, v217
	v_cvt_pk_bf16_f32 v67, v214, v216
	v_add_f32_e32 v219, v68, v69
	ds_read_b128 v[202:205], v221 offset:34848
	s_waitcnt lgkmcnt(4)
	v_mfma_f32_32x32x16_bf16 v[34:49], v[194:197], v[82:85], v[34:49]
	v_exp_f32_e32 v68, v70
	v_exp_f32_e32 v69, v71
	v_max_f32_e32 v214, v70, v71
	v_add_f32_e32 v71, v68, v69
	v_cvt_pk_bf16_f32 v68, v68, v69
	ds_read_b128 v[194:197], v221 offset:39456
	s_waitcnt lgkmcnt(4)
	v_mfma_f32_32x32x16_bf16 v[18:33], v[94:97], v[82:85], v[18:33]
	v_exp_f32_e32 v70, v72
	v_exp_f32_e32 v218, v73
	v_max_f32_e32 v69, v72, v73
	v_add_f32_e32 v72, v70, v218
	v_add_f32_e32 v73, v71, v219
	v_max3_f32 v0, v0, v214, v69
	v_add_f32_e32 v73, v72, v73
	v_cvt_pk_bf16_f32 v69, v70, v218
	s_waitcnt lgkmcnt(3)
	v_mfma_f32_32x32x16_bf16 v[2:17], v[198:201], v[90:93], v[2:17]
	v_exp_f32_e32 v70, v74
	v_exp_f32_e32 v71, v75
	v_max_f32_e32 v94, v74, v75
	v_add_f32_e32 v75, v70, v71
	v_cvt_pk_bf16_f32 v70, v70, v71
	v_exp_f32_e32 v74, v76
	v_exp_f32_e32 v72, v77
	v_max_f32_e32 v71, v76, v77
	v_add_f32_e32 v76, v74, v72
	v_add_f32_e32 v77, v75, v73
	v_max3_f32 v0, v0, v94, v71
	v_add_f32_e32 v95, v76, v77
	v_cvt_pk_bf16_f32 v71, v74, v72
	ds_read_b128 v[74:77], v221 offset:30272
	s_waitcnt lgkmcnt(3)
	v_mfma_f32_32x32x16_bf16 v[50:65], v[86:89], v[90:93], v[50:65]
	ds_read_b128 v[82:85], v221 offset:25664
	ds_read_b128 v[86:89], v221 offset:34880
	s_waitcnt lgkmcnt(4)
	v_mfma_f32_32x32x16_bf16 v[34:49], v[202:205], v[90:93], v[34:49]
	v_exp_f32_e32 v72, v78
	v_exp_f32_e32 v73, v79
	v_max_f32_e32 v198, v78, v79
	v_add_f32_e32 v79, v72, v73
	v_cvt_pk_bf16_f32 v72, v72, v73
	s_waitcnt lgkmcnt(2)
	v_mfma_f32_32x32x16_bf16 v[50:65], v[74:77], v[66:69], v[50:65]
	ds_read_b128 v[74:77], v221 offset:34912
	v_mfma_f32_32x32x16_bf16 v[18:33], v[194:197], v[90:93], v[18:33]
	v_exp_f32_e32 v78, v80
	v_exp_f32_e32 v94, v81
	v_max_f32_e32 v194, v80, v81
	v_pk_add_f32 v[96:97], v[78:79], v[94:95]
	v_cvt_pk_bf16_f32 v73, v78, v94
	ds_read_b128 v[78:81], v221 offset:25696
	s_waitcnt lgkmcnt(3)
	v_mfma_f32_32x32x16_bf16 v[2:17], v[82:85], v[66:69], v[2:17]
	ds_read_b128 v[82:85], v221 offset:39488
	ds_read_b128 v[90:93], v221 offset:30304
	s_waitcnt lgkmcnt(4)
	v_mfma_f32_32x32x16_bf16 v[34:49], v[86:89], v[66:69], v[34:49]
	ds_read_b128 v[86:89], v221 offset:39520
	v_max3_f32 v0, v0, v198, v194
	ds_bpermute_b32 v244, v191, v0
	v_add_f32_e32 v245, v96, v97
	v_add_f32_e32 v193, v193, v245
	s_xor_b32 s28, s40, 1
	s_mul_i32 s28, s28, 0xac00
	v_add3_u32 v246, s28, v169, v181
	v_add3_u32 v247, s28, v182, v183
	v_add3_u32 v248, s28, v184, v185
	v_add_u32_e32 v249, s28, v168
	s_waitcnt vmcnt(4)
	ds_write_b128 v246, v[146:149]
	s_waitcnt vmcnt(3)
	ds_write_b128 v247, v[150:153]
	s_waitcnt vmcnt(2)
	ds_write_b128 v248, v[154:157]
	v_add_u32_e32 v246, v249, v186
	v_add_u32_e32 v247, v249, v187
	s_waitcnt vmcnt(1)
	ds_write_b128 v246, v[158:161] offset:25600
	s_waitcnt vmcnt(0)
	ds_write_b128 v247, v[162:165] offset:25600
	s_waitcnt lgkmcnt(8)
	v_mfma_f32_32x32x16_bf16 v[18:33], v[82:85], v[66:69], v[18:33]
	v_mfma_f32_32x32x16_bf16 v[2:17], v[78:81], v[70:73], v[2:17]
	s_waitcnt lgkmcnt(7)
	v_mfma_f32_32x32x16_bf16 v[50:65], v[90:93], v[70:73], v[50:65]
	v_mfma_f32_32x32x16_bf16 v[34:49], v[74:77], v[70:73], v[34:49]
	s_waitcnt lgkmcnt(6)
	v_mfma_f32_32x32x16_bf16 v[18:33], v[86:89], v[70:73], v[18:33]
	s_waitcnt lgkmcnt(0)
	v_max_f32_e32 v244, v244, v244
	v_max_f32_e32 v0, v0, v244
	v_cmp_lt_f32_e32 vcc, s87, v0
	s_cbranch_vccz .LBB0_113
	v_max_f32_e32 v0, v0, v0
	v_max_f32_e32 v66, 0, v0
	v_exp_f32_e64 v0, -v66
	v_add_f32_e32 v192, v192, v66
	v_xor_b32_e32 v228, 0x80000000, v192
	v_mov_b32_e32 v229, v228
	v_mov_b32_e32 v230, v228
	v_mov_b32_e32 v231, v228
	v_mov_b32_e32 v232, v228
	v_mov_b32_e32 v233, v228
	v_mov_b32_e32 v234, v228
	v_mov_b32_e32 v235, v228
	v_mov_b32_e32 v236, v228
	v_mov_b32_e32 v237, v228
	v_mov_b32_e32 v238, v228
	v_mov_b32_e32 v239, v228
	v_mov_b32_e32 v240, v228
	v_mov_b32_e32 v241, v228
	v_mov_b32_e32 v242, v228
	v_mov_b32_e32 v243, v228
	v_mul_f32_e32 v193, v193, v0
	v_pk_mul_f32 v[16:17], v[16:17], v[0:1] op_sel_hi:[1,0]
	v_pk_mul_f32 v[14:15], v[14:15], v[0:1] op_sel_hi:[1,0]
	v_pk_mul_f32 v[12:13], v[12:13], v[0:1] op_sel_hi:[1,0]
	v_pk_mul_f32 v[10:11], v[10:11], v[0:1] op_sel_hi:[1,0]
	v_pk_mul_f32 v[8:9], v[8:9], v[0:1] op_sel_hi:[1,0]
	v_pk_mul_f32 v[6:7], v[6:7], v[0:1] op_sel_hi:[1,0]
	v_pk_mul_f32 v[4:5], v[4:5], v[0:1] op_sel_hi:[1,0]
	v_pk_mul_f32 v[2:3], v[2:3], v[0:1] op_sel_hi:[1,0]
	v_pk_mul_f32 v[64:65], v[64:65], v[0:1] op_sel_hi:[1,0]
	v_pk_mul_f32 v[62:63], v[62:63], v[0:1] op_sel_hi:[1,0]
	v_pk_mul_f32 v[60:61], v[60:61], v[0:1] op_sel_hi:[1,0]
	v_pk_mul_f32 v[58:59], v[58:59], v[0:1] op_sel_hi:[1,0]
	v_pk_mul_f32 v[56:57], v[56:57], v[0:1] op_sel_hi:[1,0]
	v_pk_mul_f32 v[54:55], v[54:55], v[0:1] op_sel_hi:[1,0]
	v_pk_mul_f32 v[52:53], v[52:53], v[0:1] op_sel_hi:[1,0]
	v_pk_mul_f32 v[50:51], v[50:51], v[0:1] op_sel_hi:[1,0]
	v_pk_mul_f32 v[48:49], v[48:49], v[0:1] op_sel_hi:[1,0]
	v_pk_mul_f32 v[46:47], v[46:47], v[0:1] op_sel_hi:[1,0]
	v_pk_mul_f32 v[44:45], v[44:45], v[0:1] op_sel_hi:[1,0]
	v_pk_mul_f32 v[42:43], v[42:43], v[0:1] op_sel_hi:[1,0]
	v_pk_mul_f32 v[40:41], v[40:41], v[0:1] op_sel_hi:[1,0]
	v_pk_mul_f32 v[38:39], v[38:39], v[0:1] op_sel_hi:[1,0]
	v_pk_mul_f32 v[36:37], v[36:37], v[0:1] op_sel_hi:[1,0]
	v_pk_mul_f32 v[34:35], v[34:35], v[0:1] op_sel_hi:[1,0]
	v_pk_mul_f32 v[32:33], v[32:33], v[0:1] op_sel_hi:[1,0]
	v_pk_mul_f32 v[30:31], v[30:31], v[0:1] op_sel_hi:[1,0]
	v_pk_mul_f32 v[28:29], v[28:29], v[0:1] op_sel_hi:[1,0]
	v_pk_mul_f32 v[26:27], v[26:27], v[0:1] op_sel_hi:[1,0]
	v_pk_mul_f32 v[24:25], v[24:25], v[0:1] op_sel_hi:[1,0]
	v_pk_mul_f32 v[22:23], v[22:23], v[0:1] op_sel_hi:[1,0]
	v_pk_mul_f32 v[20:21], v[20:21], v[0:1] op_sel_hi:[1,0]
	v_pk_mul_f32 v[18:19], v[18:19], v[0:1] op_sel_hi:[1,0]
